# P3: pool blocks 3 pool items first; sample blocks 4 samples then 1 pool item last
# baseline (speedup 1.0000x reference)
; #define OPAQUE_TID() int tid = threadIdx.x; asm volatile("" : "+v"(tid)); const int lane = tid & 63, wave = __builtin_amdgcn_readfirstlane(tid >> 6); (void)lane; (void)wave
; __device__ __forceinline__ void pool_prepass(const Args& a) {
;     OPAQUE_TID();
;     const bf16_t* U = (const bf16_t*)(a.ws + WS_U);
;     bf16_t* PB = (bf16_t*)a.out;
;     const int G = gridDim.x, gq = wave & 3, ch = gq * 256 + (lane & 31) * 8;
;     for (int it = blockIdx.x; it < MT / 64; it += G) {
;         const int row0 = (it * 4 + (wave >> 2) * 2 + (lane >> 5)) * 16;
;         if (gq == 0) pool_run<2>(a, U, PB, row0, ch);
;         else if (gq == 1) pool_run<4>(a, U, PB, row0, ch);
;         else if (gq == 2) pool_run<8>(a, U, PB, row0, ch);
;         else pool_run<16>(a, U, PB, row0, ch);
;     }
; __global__ void __launch_bounds__(512, 2) fwd_megakernel(Args a) {
;     ...
;         if ((bid >> 5) & 1) pool_prepass(a);
.LBB0_341:
	s_or_b64 exec, exec, s[0:1]
	s_bitcmp0_b32 s2, 5
	s_cselect_b64 s[40:41], -1, 0
	s_and_b64 vcc, exec, s[40:41]
	s_waitcnt lgkmcnt(0)
	s_barrier
	s_cbranch_vccnz .LBB0_642
	s_and_b32 s98, s2, 31
	s_lshr_b32 s99, s2, 6
	s_lshl_b32 s99, s99, 5
	s_or_b32 s98, s98, s99
	s_movk_i32 s99, 0x80
	v_mov_b32_e32 v0, v180
	s_cmpk_gt_i32 s98, 0x17f
	v_readfirstlane_b32 s0, v0
	s_cbranch_scc1 .LBB0_642
	v_lshlrev_b32_e32 v1, 3, v0
	s_bfe_u32 s12, s0, 0x20006
	v_and_b32_e32 v1, 0xf8, v1
	s_ashr_i32 s0, s0, 7
	v_lshl_or_b32 v124, s12, 8, v1
	s_and_b32 s0, s0, -2
	s_lshl_b32 s1, s98, 2
	v_bfe_u32 v125, v0, 5, 1
	v_mov_b32_e32 v127, 0
	v_lshlrev_b32_e32 v126, 1, v124
	s_add_i32 s13, s1, s0
	v_lshl_add_u64 v[128:129], s[28:29], 0, v[126:127]
	v_lshl_add_u64 v[130:131], s[26:27], 0, v[126:127]
	v_lshlrev_b32_e32 v126, 2, v124
	v_or_b32_e32 v0, s13, v125
	v_lshl_add_u64 v[132:133], s[44:45], 0, v[126:127]
	s_lshl_b32 s14, s99, 2
	v_lshl_or_b32 v134, v0, 4, 15
	s_lshl_b32 s15, s99, 6
	s_movk_i32 s42, 0x7ff
	v_mov_b32_e32 v139, 0xfffff80f
	v_not_b32_e32 v170, 16
	v_mov_b32_e32 v171, 0x7ff
	s_movk_i32 s43, 0x3800
	s_mov_b32 s52, 0x3d800000
	s_mov_b32 s53, 0x3e000000
	s_mov_b32 s54, 0x3e800000
	v_mov_b32_e32 v172, 0x7f1
	v_mov_b32_e32 v173, 0x2100000
	v_mov_b32_e32 v174, 0x2540040
	v_mov_b32_e32 v175, 0x41800000
	v_mov_b32_e32 v176, 0x41000000
	s_mov_b32 s55, s98
	s_branch .LBB0_345
.LBB0_344:
	s_or_b64 exec, exec, s[0:1]
	s_add_i32 s55, s55, s99
	s_add_i32 s13, s13, s14
	s_cmpk_lt_i32 s55, 0x180
	v_add_u32_e32 v134, s15, v134
	s_cbranch_scc0 .LBB0_642

; #define OPAQUE_TID() int tid = threadIdx.x; asm volatile("" : "+v"(tid)); const int lane = tid & 63, wave = __builtin_amdgcn_readfirstlane(tid >> 6); (void)lane; (void)wave
; __device__ __forceinline__ void pool_prepass(const Args& a) {
;     OPAQUE_TID();
;     const bf16_t* U = (const bf16_t*)(a.ws + WS_U);
;     bf16_t* PB = (bf16_t*)a.out;
;     const int G = gridDim.x, gq = wave & 3, ch = gq * 256 + (lane & 31) * 8;
;     for (int it = blockIdx.x; it < MT / 64; it += G) {
;         const int row0 = (it * 4 + (wave >> 2) * 2 + (lane >> 5)) * 16;
;         if (gq == 0) pool_run<2>(a, U, PB, row0, ch);
;         else if (gq == 1) pool_run<4>(a, U, PB, row0, ch);
;         else if (gq == 2) pool_run<8>(a, U, PB, row0, ch);
;         else pool_run<16>(a, U, PB, row0, ch);
;     }
; __global__ void __launch_bounds__(512, 2) fwd_megakernel(Args a) {
;     ...
;         if (!((bid >> 5) & 1)) pool_prepass(a);
.LBB0_775:
	s_and_b64 vcc, exec, s[40:41]
	s_cbranch_vccz .LBB0_1076
	v_mov_b32_e32 v0, v180
	s_and_b32 s98, s2, 31
	s_lshr_b32 s99, s2, 6
	s_lshl_b32 s99, s99, 5
	s_or_b32 s98, s98, s99
	s_addk_i32 s98, 0x180
	s_movk_i32 s99, 0x80
	s_cmpk_gt_i32 s98, 0x20f
	v_readfirstlane_b32 s0, v0
	s_cbranch_scc1 .LBB0_1076
	v_lshlrev_b32_e32 v1, 3, v0
	s_bfe_u32 s12, s0, 0x20006
	v_and_b32_e32 v1, 0xf8, v1
	s_ashr_i32 s0, s0, 7
	v_lshl_or_b32 v124, s12, 8, v1
	s_and_b32 s0, s0, -2
	s_lshl_b32 s1, s98, 2
	v_bfe_u32 v125, v0, 5, 1
	v_mov_b32_e32 v127, 0
	v_lshlrev_b32_e32 v126, 1, v124
	s_add_i32 s13, s1, s0
	v_lshl_add_u64 v[128:129], s[28:29], 0, v[126:127]
	v_lshl_add_u64 v[130:131], s[26:27], 0, v[126:127]
	v_lshlrev_b32_e32 v126, 2, v124
	v_or_b32_e32 v0, s13, v125
	v_lshl_add_u64 v[132:133], s[44:45], 0, v[126:127]
	s_lshl_b32 s14, s99, 2
	v_lshl_or_b32 v134, v0, 4, 15
	s_lshl_b32 s15, s99, 6
	s_movk_i32 s40, 0x7ff
	v_mov_b32_e32 v139, 0xfffff80f
	v_not_b32_e32 v170, 16
	v_mov_b32_e32 v171, 0x7ff
	s_movk_i32 s41, 0x3800
	s_mov_b32 s42, 0x3d800000
	s_mov_b32 s43, 0x3e000000
	s_mov_b32 s44, 0x3e800000
	v_mov_b32_e32 v172, 0x7f1
	v_mov_b32_e32 v173, 0x2100000
	v_mov_b32_e32 v174, 0x2540040
	v_mov_b32_e32 v175, 0x41800000
	v_mov_b32_e32 v176, 0x41000000
	s_mov_b32 s45, s98
	s_branch .LBB0_779
.LBB0_778:
	s_or_b64 exec, exec, s[0:1]
	s_add_i32 s45, s45, s99
	s_add_i32 s13, s13, s14
	s_cmpk_lt_i32 s45, 0x210
	v_add_u32_e32 v134, s15, v134
	s_cbranch_scc0 .LBB0_1076
